# v027 plus nt hint on the wide prologue stores (cos/sin DFT table, context K caches)
# baseline (speedup 1.0000x reference)
.LBB0_15:
	v_alignbit_b32 v11, v9, v8, 9
	v_and_b32_e32 v6, 0xff8, v10
	v_lshrrev_b64 v[12:13], 9, v[8:9]
	v_mad_u32_u24 v15, v6, v11, v11
	v_lshlrev_b64 v[12:13], 14, v[12:13]
	v_and_b32_e32 v17, 0xfff, v15
	v_add_u32_e32 v18, 0x400, v15
	v_add_u32_e32 v15, v15, v11
	v_mul_u32_u24_e32 v14, v6, v11
	v_mad_u32_u24 v16, v6, v11, s38
	v_lshlrev_b32_e32 v6, 1, v6
	v_lshl_add_u64 v[12:13], s[6:7], 0, v[12:13]
	v_and_b32_e32 v19, 0xffe, v15
	v_add_u32_e32 v22, v15, v11
	v_and_b32_e32 v18, 0xfff, v18
	v_lshl_add_u64 v[20:21], v[12:13], 0, v[6:7]
	v_lshl_add_u32 v13, v19, 2, 0
	v_add_u32_e32 v19, v22, v11
	v_and_b32_e32 v14, 0xff8, v14
	v_and_b32_e32 v16, 0xff8, v16
	v_add_u32_e32 v15, 0x400, v15
	v_lshl_add_u32 v6, v18, 2, 0
	v_add_u32_e32 v18, 0x400, v22
	v_add_u32_e32 v25, v19, v11
	v_lshl_add_u32 v14, v14, 2, 0
	v_lshl_add_u32 v17, v17, 2, 0
	v_lshl_add_u32 v16, v16, 2, 0
	v_and_b32_e32 v12, 0xfff, v22
	v_and_b32_e32 v15, 0xffe, v15
	v_and_b32_e32 v18, 0xfff, v18
	v_and_b32_e32 v26, 0xfff, v25
	v_add_u32_e32 v27, 0x400, v25
	v_add_u32_e32 v25, v25, v11
	ds_read_b32 v14, v14
	ds_read_b32 v17, v17
	ds_read_b32 v16, v16
	ds_read_b32 v6, v6
	ds_read_b32 v13, v13
	v_lshl_add_u32 v12, v12, 2, 0
	v_lshl_add_u32 v15, v15, 2, 0
	v_and_b32_e32 v24, 0xffc, v19
	v_add_u32_e32 v19, 0x400, v19
	v_lshl_add_u32 v18, v18, 2, 0
	v_add_u32_e32 v11, v25, v11
	v_and_b32_e32 v19, 0xffc, v19
	ds_read_b32 v28, v12
	ds_read_b32 v15, v15
	ds_read_b32 v18, v18
	v_lshl_add_u32 v12, v26, 2, 0
	v_and_b32_e32 v26, 0xfff, v27
	v_and_b32_e32 v27, 0xffe, v25
	v_and_b32_e32 v30, 0xfff, v11
	v_add_u32_e32 v11, 0x400, v11
	v_lshl_add_u32 v24, v24, 2, 0
	v_lshl_add_u32 v19, v19, 2, 0
	v_add_u32_e32 v25, 0x400, v25
	v_lshl_add_u32 v26, v26, 2, 0
	v_lshl_add_u32 v27, v27, 2, 0
	v_and_b32_e32 v11, 0xfff, v11
	ds_read_b32 v24, v24
	ds_read_b32 v29, v12
	ds_read_b32 v19, v19
	v_and_b32_e32 v25, 0xffe, v25
	s_waitcnt lgkmcnt(9)
	v_cvt_pk_bf16_f32 v12, v14, v17
	ds_read_b32 v26, v26
	ds_read_b32 v27, v27
	v_lshl_add_u32 v14, v30, 2, 0
	v_lshl_add_u32 v11, v11, 2, 0
	v_lshl_add_u32 v17, v25, 2, 0
	s_waitcnt lgkmcnt(9)
	v_cvt_pk_bf16_f32 v16, v16, v6
	ds_read_b32 v6, v14
	ds_read_b32 v25, v17
	ds_read_b32 v11, v11
	v_lshl_add_u64 v[8:9], v[8:9], 0, s[34:35]
	v_cmp_lt_u64_e32 vcc, s[10:11], v[8:9]
	v_add_u32_e32 v10, s33, v10
	s_or_b64 s[8:9], vcc, s[8:9]
	v_add_co_u32_e32 v22, vcc, 0x2000, v20
	s_waitcnt lgkmcnt(10)
	v_cvt_pk_bf16_f32 v13, v13, v28
	s_waitcnt lgkmcnt(8)
	v_cvt_pk_bf16_f32 v17, v15, v18
	s_waitcnt lgkmcnt(6)
	v_cvt_pk_bf16_f32 v14, v24, v29
	s_waitcnt lgkmcnt(2)
	v_cvt_pk_bf16_f32 v15, v27, v6
	v_addc_co_u32_e32 v23, vcc, 0, v21, vcc
	v_cvt_pk_bf16_f32 v18, v19, v26
	s_waitcnt lgkmcnt(0)
	v_cvt_pk_bf16_f32 v19, v25, v11
	global_store_dwordx4 v[20:21], v[12:15], off nt
	global_store_dwordx4 v[22:23], v[16:19], off nt
	s_andn2_b64 exec, exec, s[8:9]
	s_cbranch_execnz .LBB0_15

.LBB0_49:
	v_lshl_add_u64 v[20:21], s[12:13], 0, v[10:11]
	v_lshl_add_u64 v[22:23], s[16:17], 0, v[10:11]
	global_load_dwordx4 v[12:15], v[20:21], off
	global_load_dwordx4 v[16:19], v[22:23], off
	v_add_co_u32_e32 v20, vcc, 0xff800000, v6
	v_lshl_add_u64 v[4:5], v[4:5], 0, s[34:35]
	s_nop 0
	v_addc_co_u32_e32 v21, vcc, -1, v7, vcc
	v_cmp_lt_u64_e32 vcc, s[10:11], v[4:5]
	v_lshl_add_u64 v[10:11], v[10:11], 0, s[4:5]
	s_or_b64 s[8:9], vcc, s[8:9]
	s_waitcnt vmcnt(1)
	v_cvt_pk_bf16_f32 v12, v12, v13
	v_cvt_pk_bf16_f32 v13, v14, v15
	s_waitcnt vmcnt(0)
	v_cvt_pk_bf16_f32 v14, v16, v17
	v_cvt_pk_bf16_f32 v15, v18, v19
	global_store_dwordx2 v[20:21], v[12:13], off nt
	global_store_dwordx2 v[6:7], v[14:15], off nt
	v_lshl_add_u64 v[6:7], v[6:7], 0, v[8:9]
	s_andn2_b64 exec, exec, s[8:9]
	s_cbranch_execnz .LBB0_49
